# GEMM K-loop back edge: pointer/counter SALU block hoisted above the loop-back barrier so only the branch follows the barrier release
# baseline (speedup 1.0000x reference)
.LBB0_87:
	ds_read_b128 v[136:139], v178
	ds_read_b128 v[140:143], v178 offset:1024
	ds_read_b128 v[144:147], v178 offset:2048
	ds_read_b128 v[148:151], v178 offset:3072
	ds_read_b128 v[166:169], v179
	ds_read_b128 v[170:173], v179 offset:1024
	ds_read_b128 v[184:187], v179 offset:2048
	ds_read_b128 v[188:191], v179 offset:3072
	s_add_i32 s30, s8, 2
	s_add_u32 s31, s2, 0x80
	s_addc_u32 s9, s3, 0
	s_cmp_eq_u32 s24, s8
	s_cselect_b32 s8, s0, s31
	s_cselect_b32 s9, s1, s9
	s_cselect_b32 s35, s29, s27
	s_cselect_b32 s34, s28, s11
	v_lshl_add_u64 v[224:225], s[2:3], 0, v[134:135]
	s_add_i32 m0, s72, 0xc000
	ds_read_b128 v[192:195], v180
	ds_read_b128 v[196:199], v180 offset:1024
	ds_read_b128 v[200:203], v180 offset:2048
	ds_read_b128 v[204:207], v180 offset:3072
	ds_read_b128 v[208:211], v180 offset:4096
	ds_read_b128 v[212:215], v180 offset:5120
	ds_read_b128 v[216:219], v180 offset:6144
	ds_read_b128 v[220:223], v180 offset:7168
	global_load_lds_dwordx4 v[224:225], off
	v_lshl_add_u64 v[224:225], s[2:3], 0, v[132:133]
	s_add_i32 m0, s72, 0xe000
	s_nop 0
	global_load_lds_dwordx4 v[224:225], off
	s_waitcnt vmcnt(8)
	s_waitcnt lgkmcnt(0)
	s_barrier
	s_setprio 1
	s_waitcnt lgkmcnt(0)
	v_mfma_f32_16x16x32_bf16 v[124:127], v[136:139], v[192:195], v[124:127]
	v_mfma_f32_16x16x32_bf16 v[120:123], v[144:147], v[192:195], v[120:123]
	v_mfma_f32_16x16x32_bf16 v[108:111], v[136:139], v[200:203], v[108:111]
	v_mfma_f32_16x16x32_bf16 v[104:107], v[144:147], v[200:203], v[104:107]
	v_mfma_f32_16x16x32_bf16 v[92:95], v[136:139], v[208:211], v[92:95]
	v_mfma_f32_16x16x32_bf16 v[88:91], v[144:147], v[208:211], v[88:91]
	v_mfma_f32_16x16x32_bf16 v[76:79], v[136:139], v[216:219], v[76:79]
	v_mfma_f32_16x16x32_bf16 v[72:75], v[144:147], v[216:219], v[72:75]
	v_mfma_f32_16x16x32_bf16 v[124:127], v[140:143], v[196:199], v[124:127]
	v_mfma_f32_16x16x32_bf16 v[120:123], v[148:151], v[196:199], v[120:123]
	v_mfma_f32_16x16x32_bf16 v[108:111], v[140:143], v[204:207], v[108:111]
	v_mfma_f32_16x16x32_bf16 v[104:107], v[148:151], v[204:207], v[104:107]
	v_mfma_f32_16x16x32_bf16 v[92:95], v[140:143], v[212:215], v[92:95]
	v_mfma_f32_16x16x32_bf16 v[88:91], v[148:151], v[212:215], v[88:91]
	v_mfma_f32_16x16x32_bf16 v[76:79], v[140:143], v[220:223], v[76:79]
	v_mfma_f32_16x16x32_bf16 v[72:75], v[148:151], v[220:223], v[72:75]
	s_setprio 0
	s_setprio 1
	v_mfma_f32_16x16x32_bf16 v[116:119], v[166:169], v[192:195], v[116:119]
	v_mfma_f32_16x16x32_bf16 v[112:115], v[184:187], v[192:195], v[112:115]
	v_mfma_f32_16x16x32_bf16 v[100:103], v[166:169], v[200:203], v[100:103]
	v_mfma_f32_16x16x32_bf16 v[96:99], v[184:187], v[200:203], v[96:99]
	v_mfma_f32_16x16x32_bf16 v[84:87], v[166:169], v[208:211], v[84:87]
	v_mfma_f32_16x16x32_bf16 v[80:83], v[184:187], v[208:211], v[80:83]
	v_mfma_f32_16x16x32_bf16 v[68:71], v[166:169], v[216:219], v[68:71]
	v_mfma_f32_16x16x32_bf16 v[64:67], v[184:187], v[216:219], v[64:67]
	v_mfma_f32_16x16x32_bf16 v[116:119], v[170:173], v[196:199], v[116:119]
	v_mfma_f32_16x16x32_bf16 v[112:115], v[188:191], v[196:199], v[112:115]
	v_mfma_f32_16x16x32_bf16 v[100:103], v[170:173], v[204:207], v[100:103]
	v_mfma_f32_16x16x32_bf16 v[96:99], v[188:191], v[204:207], v[96:99]
	v_mfma_f32_16x16x32_bf16 v[84:87], v[170:173], v[212:215], v[84:87]
	v_mfma_f32_16x16x32_bf16 v[80:83], v[188:191], v[212:215], v[80:83]
	v_mfma_f32_16x16x32_bf16 v[68:71], v[170:173], v[220:223], v[68:71]
	v_mfma_f32_16x16x32_bf16 v[64:67], v[188:191], v[220:223], v[64:67]
	s_setprio 0
	s_barrier
	s_mov_b32 m0, s68
	v_lshl_add_u64 v[224:225], s[34:35], 0, v[128:129]
	v_lshl_add_u64 v[230:231], s[34:35], 0, v[130:131]
	s_add_u32 s34, s34, s20
	ds_read_b128 v[192:195], v180 offset:16384
	ds_read_b128 v[196:199], v180 offset:17408
	ds_read_b128 v[200:203], v180 offset:18432
	ds_read_b128 v[204:207], v180 offset:19456
	ds_read_b128 v[208:211], v180 offset:20480
	ds_read_b128 v[212:215], v180 offset:21504
	ds_read_b128 v[216:219], v180 offset:22528
	ds_read_b128 v[220:223], v180 offset:23552
	global_load_lds_dwordx4 v[224:225], off
	s_mov_b32 m0, s69
	s_addc_u32 s35, s35, 0
	global_load_lds_dwordx4 v[230:231], off
	v_lshl_add_u64 v[232:233], s[34:35], 0, v[128:129]
	s_mov_b32 m0, s70
	v_lshl_add_u64 v[234:235], s[34:35], 0, v[130:131]
	global_load_lds_dwordx4 v[232:233], off
	s_mov_b32 m0, s71
	v_lshl_add_u64 v[236:237], s[8:9], 0, v[128:129]
	global_load_lds_dwordx4 v[234:235], off
	s_mov_b32 m0, s72
	v_lshl_add_u64 v[244:245], s[8:9], 0, v[130:131]
	global_load_lds_dwordx4 v[236:237], off
	s_mov_b32 m0, s73
	s_nop 0
	global_load_lds_dwordx4 v[244:245], off
	s_waitcnt vmcnt(8)
	s_waitcnt lgkmcnt(0)
	s_barrier
	s_setprio 1
	s_waitcnt lgkmcnt(0)
	v_mfma_f32_16x16x32_bf16 v[60:63], v[136:139], v[192:195], v[60:63]
	v_mfma_f32_16x16x32_bf16 v[56:59], v[144:147], v[192:195], v[56:59]
	v_mfma_f32_16x16x32_bf16 v[44:47], v[136:139], v[200:203], v[44:47]
	v_mfma_f32_16x16x32_bf16 v[40:43], v[144:147], v[200:203], v[40:43]
	v_mfma_f32_16x16x32_bf16 v[28:31], v[136:139], v[208:211], v[28:31]
	v_mfma_f32_16x16x32_bf16 v[24:27], v[144:147], v[208:211], v[24:27]
	v_mfma_f32_16x16x32_bf16 v[12:15], v[136:139], v[216:219], v[12:15]
	v_mfma_f32_16x16x32_bf16 v[8:11], v[144:147], v[216:219], v[8:11]
	v_mfma_f32_16x16x32_bf16 v[60:63], v[140:143], v[196:199], v[60:63]
	v_mfma_f32_16x16x32_bf16 v[56:59], v[148:151], v[196:199], v[56:59]
	v_mfma_f32_16x16x32_bf16 v[44:47], v[140:143], v[204:207], v[44:47]
	v_mfma_f32_16x16x32_bf16 v[40:43], v[148:151], v[204:207], v[40:43]
	v_mfma_f32_16x16x32_bf16 v[28:31], v[140:143], v[212:215], v[28:31]
	v_mfma_f32_16x16x32_bf16 v[24:27], v[148:151], v[212:215], v[24:27]
	v_mfma_f32_16x16x32_bf16 v[12:15], v[140:143], v[220:223], v[12:15]
	v_mfma_f32_16x16x32_bf16 v[8:11], v[148:151], v[220:223], v[8:11]
	s_setprio 0
	s_setprio 1
	v_mfma_f32_16x16x32_bf16 v[52:55], v[166:169], v[192:195], v[52:55]
	v_mfma_f32_16x16x32_bf16 v[48:51], v[184:187], v[192:195], v[48:51]
	v_mfma_f32_16x16x32_bf16 v[36:39], v[166:169], v[200:203], v[36:39]
	v_mfma_f32_16x16x32_bf16 v[32:35], v[184:187], v[200:203], v[32:35]
	v_mfma_f32_16x16x32_bf16 v[20:23], v[166:169], v[208:211], v[20:23]
	v_mfma_f32_16x16x32_bf16 v[16:19], v[184:187], v[208:211], v[16:19]
	v_mfma_f32_16x16x32_bf16 v[4:7], v[166:169], v[216:219], v[4:7]
	v_mfma_f32_16x16x32_bf16 v[0:3], v[184:187], v[216:219], v[0:3]
	v_mfma_f32_16x16x32_bf16 v[52:55], v[170:173], v[196:199], v[52:55]
	v_mfma_f32_16x16x32_bf16 v[48:51], v[188:191], v[196:199], v[48:51]
	v_mfma_f32_16x16x32_bf16 v[36:39], v[170:173], v[204:207], v[36:39]
	v_mfma_f32_16x16x32_bf16 v[32:35], v[188:191], v[204:207], v[32:35]
	v_mfma_f32_16x16x32_bf16 v[20:23], v[170:173], v[212:215], v[20:23]
	v_mfma_f32_16x16x32_bf16 v[16:19], v[188:191], v[212:215], v[16:19]
	v_mfma_f32_16x16x32_bf16 v[4:7], v[170:173], v[220:223], v[4:7]
	v_mfma_f32_16x16x32_bf16 v[0:3], v[188:191], v[220:223], v[0:3]
	s_setprio 0
	s_barrier
	v_add_u32_e32 v152, s87, v159
	ds_read_b128 v[136:139], v181
	ds_read_b128 v[140:143], v181 offset:1024
	ds_read_b128 v[144:147], v181 offset:2048
	ds_read_b128 v[148:151], v181 offset:3072
	ds_read_b128 v[166:169], v152
	ds_read_b128 v[170:173], v152 offset:1024
	ds_read_b128 v[184:187], v152 offset:2048
	ds_read_b128 v[188:191], v152 offset:3072
	s_add_u32 s8, s8, s20
	s_addc_u32 s9, s9, 0
	s_mov_b32 m0, s74
	v_lshl_add_u64 v[246:247], s[8:9], 0, v[128:129]
	ds_read_b128 v[192:195], v180 offset:32768
	ds_read_b128 v[196:199], v180 offset:33792
	ds_read_b128 v[200:203], v180 offset:34816
	ds_read_b128 v[204:207], v180 offset:35840
	ds_read_b128 v[208:211], v180 offset:36864
	ds_read_b128 v[212:215], v180 offset:37888
	ds_read_b128 v[216:219], v180 offset:38912
	ds_read_b128 v[220:223], v180 offset:39936
	global_load_lds_dwordx4 v[246:247], off
	v_lshl_add_u64 v[246:247], s[8:9], 0, v[130:131]
	s_mov_b32 m0, s75
	s_nop 0
	global_load_lds_dwordx4 v[246:247], off
	s_waitcnt vmcnt(8)
	s_waitcnt lgkmcnt(0)
	s_barrier
	s_setprio 1
	s_waitcnt lgkmcnt(0)
	v_mfma_f32_16x16x32_bf16 v[124:127], v[136:139], v[192:195], v[124:127]
	v_mfma_f32_16x16x32_bf16 v[120:123], v[144:147], v[192:195], v[120:123]
	v_mfma_f32_16x16x32_bf16 v[108:111], v[136:139], v[200:203], v[108:111]
	v_mfma_f32_16x16x32_bf16 v[104:107], v[144:147], v[200:203], v[104:107]
	v_mfma_f32_16x16x32_bf16 v[92:95], v[136:139], v[208:211], v[92:95]
	v_mfma_f32_16x16x32_bf16 v[88:91], v[144:147], v[208:211], v[88:91]
	v_mfma_f32_16x16x32_bf16 v[76:79], v[136:139], v[216:219], v[76:79]
	v_mfma_f32_16x16x32_bf16 v[72:75], v[144:147], v[216:219], v[72:75]
	v_mfma_f32_16x16x32_bf16 v[124:127], v[140:143], v[196:199], v[124:127]
	v_mfma_f32_16x16x32_bf16 v[120:123], v[148:151], v[196:199], v[120:123]
	v_mfma_f32_16x16x32_bf16 v[108:111], v[140:143], v[204:207], v[108:111]
	v_mfma_f32_16x16x32_bf16 v[104:107], v[148:151], v[204:207], v[104:107]
	v_mfma_f32_16x16x32_bf16 v[92:95], v[140:143], v[212:215], v[92:95]
	v_mfma_f32_16x16x32_bf16 v[88:91], v[148:151], v[212:215], v[88:91]
	v_mfma_f32_16x16x32_bf16 v[76:79], v[140:143], v[220:223], v[76:79]
	v_mfma_f32_16x16x32_bf16 v[72:75], v[148:151], v[220:223], v[72:75]
	s_setprio 0
	s_setprio 1
	v_mfma_f32_16x16x32_bf16 v[116:119], v[166:169], v[192:195], v[116:119]
	v_mfma_f32_16x16x32_bf16 v[112:115], v[184:187], v[192:195], v[112:115]
	v_mfma_f32_16x16x32_bf16 v[100:103], v[166:169], v[200:203], v[100:103]
	v_mfma_f32_16x16x32_bf16 v[96:99], v[184:187], v[200:203], v[96:99]
	v_mfma_f32_16x16x32_bf16 v[84:87], v[166:169], v[208:211], v[84:87]
	v_mfma_f32_16x16x32_bf16 v[80:83], v[184:187], v[208:211], v[80:83]
	v_mfma_f32_16x16x32_bf16 v[68:71], v[166:169], v[216:219], v[68:71]
	v_mfma_f32_16x16x32_bf16 v[64:67], v[184:187], v[216:219], v[64:67]
	v_mfma_f32_16x16x32_bf16 v[116:119], v[170:173], v[196:199], v[116:119]
	v_mfma_f32_16x16x32_bf16 v[112:115], v[188:191], v[196:199], v[112:115]
	v_mfma_f32_16x16x32_bf16 v[100:103], v[170:173], v[204:207], v[100:103]
	v_mfma_f32_16x16x32_bf16 v[96:99], v[188:191], v[204:207], v[96:99]
	v_mfma_f32_16x16x32_bf16 v[84:87], v[170:173], v[212:215], v[84:87]
	v_mfma_f32_16x16x32_bf16 v[80:83], v[188:191], v[212:215], v[80:83]
	v_mfma_f32_16x16x32_bf16 v[68:71], v[170:173], v[220:223], v[68:71]
	v_mfma_f32_16x16x32_bf16 v[64:67], v[188:191], v[220:223], v[64:67]
	s_setprio 0
	s_barrier
	s_mov_b32 m0, s81
	v_lshl_add_u64 v[224:225], v[224:225], 0, s[36:37]
	ds_read_b128 v[192:195], v180 offset:49152
	ds_read_b128 v[196:199], v180 offset:50176
	ds_read_b128 v[200:203], v180 offset:51200
	ds_read_b128 v[204:207], v180 offset:52224
	ds_read_b128 v[208:211], v180 offset:53248
	ds_read_b128 v[212:215], v180 offset:54272
	ds_read_b128 v[216:219], v180 offset:55296
	ds_read_b128 v[220:223], v180 offset:56320
	global_load_lds_dwordx4 v[224:225], off
	v_lshl_add_u64 v[224:225], v[230:231], 0, s[36:37]
	s_mov_b32 m0, s84
	s_nop 0
	global_load_lds_dwordx4 v[224:225], off
	v_lshl_add_u64 v[224:225], v[232:233], 0, s[36:37]
	s_mov_b32 m0, s95
	s_nop 0
	global_load_lds_dwordx4 v[224:225], off
	v_lshl_add_u64 v[224:225], v[234:235], 0, s[36:37]
	s_mov_b32 m0, s14
	s_nop 0
	global_load_lds_dwordx4 v[224:225], off
	v_lshl_add_u64 v[224:225], v[236:237], 0, s[36:37]
	s_mov_b32 m0, s85
	s_nop 0
	global_load_lds_dwordx4 v[224:225], off
	v_lshl_add_u64 v[224:225], v[244:245], 0, s[36:37]
	s_mov_b32 m0, s86
	s_nop 0
	global_load_lds_dwordx4 v[224:225], off
	s_waitcnt vmcnt(8)
	s_waitcnt lgkmcnt(0)
	s_barrier
	s_setprio 1
	s_waitcnt lgkmcnt(0)
	v_mfma_f32_16x16x32_bf16 v[60:63], v[136:139], v[192:195], v[60:63]
	v_mfma_f32_16x16x32_bf16 v[56:59], v[144:147], v[192:195], v[56:59]
	v_mfma_f32_16x16x32_bf16 v[44:47], v[136:139], v[200:203], v[44:47]
	v_mfma_f32_16x16x32_bf16 v[40:43], v[144:147], v[200:203], v[40:43]
	v_mfma_f32_16x16x32_bf16 v[28:31], v[136:139], v[208:211], v[28:31]
	v_mfma_f32_16x16x32_bf16 v[24:27], v[144:147], v[208:211], v[24:27]
	v_mfma_f32_16x16x32_bf16 v[12:15], v[136:139], v[216:219], v[12:15]
	v_mfma_f32_16x16x32_bf16 v[8:11], v[144:147], v[216:219], v[8:11]
	v_mfma_f32_16x16x32_bf16 v[60:63], v[140:143], v[196:199], v[60:63]
	v_mfma_f32_16x16x32_bf16 v[56:59], v[148:151], v[196:199], v[56:59]
	v_mfma_f32_16x16x32_bf16 v[44:47], v[140:143], v[204:207], v[44:47]
	v_mfma_f32_16x16x32_bf16 v[40:43], v[148:151], v[204:207], v[40:43]
	v_mfma_f32_16x16x32_bf16 v[28:31], v[140:143], v[212:215], v[28:31]
	v_mfma_f32_16x16x32_bf16 v[24:27], v[148:151], v[212:215], v[24:27]
	v_mfma_f32_16x16x32_bf16 v[12:15], v[140:143], v[220:223], v[12:15]
	v_mfma_f32_16x16x32_bf16 v[8:11], v[148:151], v[220:223], v[8:11]
	s_setprio 0
	s_setprio 1
	v_mfma_f32_16x16x32_bf16 v[52:55], v[166:169], v[192:195], v[52:55]
	v_mfma_f32_16x16x32_bf16 v[48:51], v[184:187], v[192:195], v[48:51]
	v_mfma_f32_16x16x32_bf16 v[36:39], v[166:169], v[200:203], v[36:39]
	v_mfma_f32_16x16x32_bf16 v[32:35], v[184:187], v[200:203], v[32:35]
	v_mfma_f32_16x16x32_bf16 v[20:23], v[166:169], v[208:211], v[20:23]
	v_mfma_f32_16x16x32_bf16 v[16:19], v[184:187], v[208:211], v[16:19]
	v_mfma_f32_16x16x32_bf16 v[4:7], v[166:169], v[216:219], v[4:7]
	v_mfma_f32_16x16x32_bf16 v[0:3], v[184:187], v[216:219], v[0:3]
	v_mfma_f32_16x16x32_bf16 v[52:55], v[170:173], v[196:199], v[52:55]
	v_mfma_f32_16x16x32_bf16 v[48:51], v[188:191], v[196:199], v[48:51]
	v_mfma_f32_16x16x32_bf16 v[36:39], v[170:173], v[204:207], v[36:39]
	v_mfma_f32_16x16x32_bf16 v[32:35], v[188:191], v[204:207], v[32:35]
	v_mfma_f32_16x16x32_bf16 v[20:23], v[170:173], v[212:215], v[20:23]
	v_mfma_f32_16x16x32_bf16 v[16:19], v[188:191], v[212:215], v[16:19]
	v_mfma_f32_16x16x32_bf16 v[4:7], v[170:173], v[220:223], v[4:7]
	v_mfma_f32_16x16x32_bf16 v[0:3], v[188:191], v[220:223], v[0:3]
	s_setprio 0
	s_add_u32 s11, s11, 0x100
	s_addc_u32 s27, s27, 0
	s_add_u32 s2, s2, 0x100
	s_addc_u32 s3, s3, 0
	s_cmp_ge_u32 s30, s15
	s_mov_b32 s8, s30
	s_barrier
	s_cbranch_scc0 .LBB0_87
	v_readlane_b32 s2, v254, 42
	v_readlane_b32 s3, v254, 43
	s_and_b64 vcc, exec, s[2:3]
	s_cbranch_vccz .LBB0_90
	s_barrier
